# mLSTM tile loop: decay-vector and V^T fragment LDS reads issued early into free buffers (no exposed lgkmcnt(0) round trips)
# speedup vs baseline: 1.0113x; 1.0042x over previous
.LBB0_326:
	ds_read_b128 v[236:239], v181
	ds_read_b128 v[240:243], v181 offset:8448
	ds_read_b128 v[244:247], v181 offset:64
	ds_read_b128 v[248:251], v181 offset:8512
	ds_read_b128 v[206:209], v181 offset:128
	ds_read_b128 v[210:213], v181 offset:8576
	v_cmp_le_i32_e32 vcc, v180, v130
	v_add_u32_e32 v192, 2, v180
	v_cmp_le_i32_e64 s[34:35], v192, v130
	v_add_u32_e32 v183, -1, v183
	s_waitcnt vmcnt(23) lgkmcnt(5)
	v_mfma_f32_16x16x32_bf16 v[198:201], v[236:239], v[116:119], 0
	s_waitcnt lgkmcnt(4)
	v_mfma_f32_16x16x32_bf16 v[124:127], v[240:243], v[116:119], 0
	ds_read_b128 v[236:239], v181 offset:192
	ds_read_b128 v[240:243], v181 offset:8640
	s_waitcnt vmcnt(22) lgkmcnt(5)
	v_mfma_f32_16x16x32_bf16 v[198:201], v[244:247], v[112:115], v[198:201]
	s_waitcnt lgkmcnt(4)
	v_mfma_f32_16x16x32_bf16 v[124:127], v[248:251], v[112:115], v[124:127]
	ds_read_b128 v[244:247], v181 offset:256
	ds_read_b128 v[248:251], v181 offset:8704
	s_waitcnt vmcnt(21) lgkmcnt(5)
	v_mfma_f32_16x16x32_bf16 v[198:201], v[206:209], v[108:111], v[198:201]
	s_waitcnt lgkmcnt(4)
	v_mfma_f32_16x16x32_bf16 v[124:127], v[210:213], v[108:111], v[124:127]
	ds_read_b128 v[206:209], v181 offset:320
	ds_read_b128 v[210:213], v181 offset:8768
	s_waitcnt vmcnt(20) lgkmcnt(5)
	v_mfma_f32_16x16x32_bf16 v[198:201], v[236:239], v[104:107], v[198:201]
	s_waitcnt lgkmcnt(4)
	v_mfma_f32_16x16x32_bf16 v[124:127], v[240:243], v[104:107], v[124:127]
	ds_read_b128 v[236:239], v181 offset:384
	ds_read_b128 v[240:243], v181 offset:8832
	s_waitcnt vmcnt(19) lgkmcnt(5)
	v_mfma_f32_16x16x32_bf16 v[198:201], v[244:247], v[100:103], v[198:201]
	s_waitcnt lgkmcnt(4)
	v_mfma_f32_16x16x32_bf16 v[124:127], v[248:251], v[100:103], v[124:127]
	ds_read_b128 v[244:247], v181 offset:448
	ds_read_b128 v[248:251], v181 offset:8896
	s_waitcnt vmcnt(18) lgkmcnt(5)
	v_mfma_f32_16x16x32_bf16 v[198:201], v[206:209], v[96:99], v[198:201]
	s_waitcnt lgkmcnt(4)
	v_mfma_f32_16x16x32_bf16 v[124:127], v[210:213], v[96:99], v[124:127]
	ds_read_b128 v[206:209], v179
	v_or_b32_e32 v224, 16, v180
	v_lshl_add_u32 v224, v224, 2, s53
	ds_read_b128 v[210:213], v224
	ds_read_b128 v[220:223], v182
	s_waitcnt vmcnt(17) lgkmcnt(6)
	v_mfma_f32_16x16x32_bf16 v[198:201], v[236:239], v[92:95], v[198:201]
	s_waitcnt lgkmcnt(5)
	v_mfma_f32_16x16x32_bf16 v[124:127], v[240:243], v[92:95], v[124:127]
	s_waitcnt vmcnt(16) lgkmcnt(4)
	v_mfma_f32_16x16x32_bf16 v[198:201], v[244:247], v[88:91], v[198:201]
	s_waitcnt lgkmcnt(3)
	v_mfma_f32_16x16x32_bf16 v[124:127], v[248:251], v[88:91], v[124:127]
	v_add_u32_e32 v181, 0x4200, v181
	v_add_u32_e32 v179, 0x80, v179
	s_waitcnt lgkmcnt(2)
	v_sub_f32_e32 v185, v206, v178
	v_mul_f32_e32 v185, 0x3fb8aa3b, v185
	v_exp_f32_e32 v185, v185
	v_sub_f32_e32 v194, v208, v178
	v_mul_f32_e32 v194, 0x3fb8aa3b, v194
	v_exp_f32_e32 v194, v194
	v_cndmask_b32_e32 v185, 0, v185, vcc
	v_mul_f32_e32 v191, v198, v185
	v_fmac_f32_e32 v184, v198, v185
	v_sub_f32_e32 v185, v207, v178
	v_mul_f32_e32 v185, 0x3fb8aa3b, v185
	v_exp_f32_e32 v185, v185
	v_cmp_gt_i32_e32 vcc, v130, v180
	v_cndmask_b32_e64 v195, 0, v194, s[34:35]
	v_mov_b32_e32 v198, v199
	v_cndmask_b32_e32 v194, 0, v185, vcc
	v_mov_b32_e32 v199, v200
	v_pk_mul_f32 v[198:199], v[198:199], v[194:195]
	v_or_b32_e32 v200, 3, v180
	v_add_f32_e32 v184, v198, v184
	v_add_f32_e32 v192, v199, v184
	v_sub_f32_e32 v184, v209, v178
	v_mul_f32_e32 v184, 0x3fb8aa3b, v184
	v_exp_f32_e32 v185, v184
	v_or_b32_e32 v184, 16, v180
	v_cmp_le_i32_e32 vcc, v184, v130
	s_waitcnt lgkmcnt(1)
	v_sub_f32_e32 v194, v210, v178
	v_mul_f32_e32 v194, 0x3fb8aa3b, v194
	v_exp_f32_e32 v194, v194
	s_nop 0
	v_cndmask_b32_e32 v184, 0, v194, vcc
	v_cmp_le_i32_e32 vcc, v200, v1
	v_mov_b32_e32 v200, v124
	v_or_b32_e32 v194, 17, v180
	v_cndmask_b32_e32 v185, 0, v185, vcc
	v_pk_mul_f32 v[200:201], v[200:201], v[184:185]
	v_sub_f32_e32 v184, v212, v178
	v_add_f32_e32 v124, v201, v192
	v_add_f32_e32 v192, v200, v124
	v_sub_f32_e32 v124, v211, v178
	v_mul_f32_e32 v184, 0x3fb8aa3b, v184
	v_mul_f32_e32 v124, 0x3fb8aa3b, v124
	v_exp_f32_e32 v184, v184
	v_exp_f32_e32 v124, v124
	v_or_b32_e32 v185, 18, v180
	v_cmp_le_i32_e32 vcc, v185, v1
	s_nop 1
	v_cndmask_b32_e32 v185, 0, v184, vcc
	v_cmp_le_i32_e32 vcc, v194, v130
	s_nop 1
	v_cndmask_b32_e32 v184, 0, v124, vcc
	v_mov_b32_e32 v124, v125
	v_mov_b32_e32 v125, v126
	v_pk_mul_f32 v[194:195], v[124:125], v[184:185]
	v_sub_f32_e32 v125, v213, v178
	v_mul_f32_e32 v125, 0x3fb8aa3b, v125
	v_exp_f32_e32 v125, v125
	v_add_f32_e32 v124, v194, v192
	v_add_f32_e32 v184, v195, v124
	v_add_u32_e32 v124, 19, v180
	v_cmp_le_i32_e32 vcc, v124, v130
	v_cvt_pk_bf16_f32 v126, v200, v194
	v_add_u32_e32 v180, 32, v180
	v_cndmask_b32_e32 v124, 0, v125, vcc
	v_mul_f32_e32 v185, v127, v124
	v_fmac_f32_e32 v184, v127, v124
	v_cvt_pk_bf16_f32 v127, v195, v185
	v_cvt_pk_bf16_f32 v124, v191, v198
	v_cvt_pk_bf16_f32 v125, v199, v201
	v_cmp_eq_u32_e32 vcc, 0, v183
	v_add_u32_e32 v182, 64, v182
	s_waitcnt lgkmcnt(0)
	v_mfma_f32_16x16x32_bf16 v[120:123], v[220:223], v[124:127], v[120:123]
	s_or_b64 s[46:47], vcc, s[46:47]
	s_andn2_b64 exec, exec, s[46:47]
	s_cbranch_execnz .LBB0_326
	s_or_b64 exec, exec, s[46:47]
